# T42: fused epilogue - first-half residual rows 0-9 also issued before the K-loop drain barrier (into free v144-159/v228-251), on top of T41b
# baseline (speedup 1.0000x reference)
; #define LAS __attribute__((address_space(3)))
; DI int fresh_lane() { int l; asm volatile("v_mbcnt_lo_u32_b32 %0, -1, 0\n\tv_mbcnt_hi_u32_b32 %0, -1, %0" : "=v"(l)); return l; }
; #define PG8_WAIT_V(n) asm volatile("s_waitcnt vmcnt(" #n ")" ::: "memory")
; #define PG8_BAR __builtin_amdgcn_s_barrier()
; template <class Epi, bool PERM = true, bool DBLK = false>
; __device__ __forceinline__ void gemm_phase(LAS unsigned char* lds, const Gemm g, const StaticOrder& S, const Epi& E, const int tid) {
;     ...
;     PG8_WAIT_V(0);
;     PG8_BAR;
;     DI void fused(const f32x4 (&acc)[2][2][4][2], const pg8::Unit& u, int wr, int wc, LAS unsigned char* lds) const {
;         const int lane_ = fresh_lane(), fr = lane_ & 15, fq = lane_ >> 4;
;         const int w8 = wr * 4 + wc;
; #pragma unroll
;         for (int ai = 0; ai < 2; ++ai) {
; #pragma unroll
;             for (int m = 0; m < 4; ++m)
; #pragma unroll
;                 for (int bj = 0; bj < 2; ++bj)
; #pragma unroll
;                     for (int n = 0; n < 2; ++n)
;                         *(LAS f32x4*)(lds + (size_t)(wr * 64 + m * 16 + fr) * 1040 + (bj * 128 + wc * 32 + n * 16 + 4 * fq) * 4) = acc[ai][bj][m][n];
;             __syncthreads();
;             const size_t g0 = (size_t)(u.pm * 256 + ai * 128 + w8 * 16) * DM + u.pn * 256 + lane_ * 4;
;             f32x4 xo[16];
; #pragma unroll
;             for (int rr = 0; rr < 16; ++rr) xo[rr] = *(const f32x4*)(xin + g0 + (size_t)rr * DM);
.LBB0_585:
	s_lshl_b32 s0, s62, 7
	v_mbcnt_lo_u32_b32 v130, -1, 0
	v_mbcnt_hi_u32_b32 v130, -1, v130
	s_add_i32 s0, s0, 0
	v_and_b32_e32 v131, -16, v130
	s_lshl_b32 s1, s62, 4
	v_add_u32_e32 v131, s0, v131
	s_lshl_b32 s0, s74, 8
	s_or_b32 s2, s1, s59
	s_add_i32 s18, s0, s2
	s_lshl_b32 s0, s73, 8
	v_lshlrev_b32_e32 v132, 2, v130
	s_ashr_i32 s1, s0, 31
	v_ashrrev_i32_e32 v133, 31, v132
	v_and_or_b32 v0, v130, 15, s59
	v_lshl_add_u64 v[132:133], v[132:133], 0, s[0:1]
	s_movk_i32 s0, 0x410
	s_ashr_i32 s19, s18, 31
	v_mul_lo_u32 v0, v0, s0
	s_lshl_b64 s[0:1], s[18:19], 10
	v_lshl_add_u64 v[140:141], v[132:133], 0, s[0:1]
	v_add_u32_e32 v138, v131, v0
	v_lshlrev_b64 v[142:143], 2, v[140:141]
	v_lshl_add_u64 v[252:253], s[14:15], 0, v[142:143]
	v_mov_b32_e32 v226, 0x2000
	v_mov_b32_e32 v227, 0
	global_load_dwordx4 v[144:147], v[252:253], off nt
	v_lshl_add_u64 v[252:253], v[252:253], 0, v[226:227]
	global_load_dwordx4 v[148:151], v[252:253], off offset:-4096 nt
	global_load_dwordx4 v[152:155], v[252:253], off nt
	v_lshl_add_u64 v[252:253], v[252:253], 0, v[226:227]
	global_load_dwordx4 v[156:159], v[252:253], off offset:-4096 nt
	global_load_dwordx4 v[228:231], v[252:253], off nt
	v_lshl_add_u64 v[252:253], v[252:253], 0, v[226:227]
	global_load_dwordx4 v[232:235], v[252:253], off offset:-4096 nt
	global_load_dwordx4 v[236:239], v[252:253], off nt
	v_lshl_add_u64 v[252:253], v[252:253], 0, v[226:227]
	global_load_dwordx4 v[240:243], v[252:253], off offset:-4096 nt
	global_load_dwordx4 v[244:247], v[252:253], off nt
	v_lshl_add_u64 v[252:253], v[252:253], 0, v[226:227]
	global_load_dwordx4 v[248:251], v[252:253], off offset:-4096 nt
	s_waitcnt vmcnt(10)
	s_barrier
	ds_write_b128 v138, v[126:129]
	ds_write_b128 v138, v[122:125] offset:64
	ds_write_b128 v138, v[118:121] offset:512
	ds_write_b128 v138, v[114:117] offset:576
	ds_write_b128 v138, v[110:113] offset:16640
	ds_write_b128 v138, v[106:109] offset:16704
	ds_write_b128 v138, v[102:105] offset:17152
	ds_write_b128 v138, v[98:101] offset:17216
	ds_write_b128 v138, v[94:97] offset:33280
	ds_write_b128 v138, v[90:93] offset:33344
	ds_write_b128 v138, v[86:89] offset:33792
	ds_write_b128 v138, v[82:85] offset:33856
	ds_write_b128 v138, v[78:81] offset:49920
	ds_write_b128 v138, v[74:77] offset:49984
	ds_write_b128 v138, v[70:73] offset:50432
	ds_write_b128 v138, v[66:69] offset:50496
	v_lshl_add_u64 v[66:67], s[14:15], 0, v[142:143]
	v_mov_b32_e32 v226, 0x80000
	v_mov_b32_e32 v227, 0
	v_lshl_add_u64 v[224:225], v[66:67], 0, v[226:227]
	v_mov_b32_e32 v226, 0x2000
	s_movk_i32 s80, 0x2000
	v_add_co_u32_e32 v68, vcc, s80, v66
	s_movk_i32 s81, 0x4000
	s_nop 0
	v_addc_co_u32_e32 v69, vcc, 0, v67, vcc
	v_add_co_u32_e32 v68, vcc, s81, v66
	s_movk_i32 s0, 0x6000
	s_nop 0
	v_addc_co_u32_e32 v69, vcc, 0, v67, vcc
	v_add_co_u32_e32 v68, vcc, s0, v66
	s_mov_b32 s0, 0x8000
	s_nop 0
	v_addc_co_u32_e32 v69, vcc, 0, v67, vcc
	v_add_co_u32_e32 v68, vcc, s0, v66
	s_mov_b32 s0, 0xa000
	s_nop 0
	v_addc_co_u32_e32 v69, vcc, 0, v67, vcc
	v_add_co_u32_e32 v68, vcc, s0, v66
	s_mov_b32 s0, 0xc000
	s_nop 0
	v_addc_co_u32_e32 v69, vcc, 0, v67, vcc
	global_load_dwordx4 v[86:89], v[68:69], off nt
	v_add_co_u32_e32 v68, vcc, s0, v66
	s_mov_b32 s0, 0xe000
	s_nop 0
	v_addc_co_u32_e32 v69, vcc, 0, v67, vcc
	global_load_dwordx4 v[82:85], v[68:69], off offset:-4096 nt
	global_load_dwordx4 v[78:81], v[68:69], off nt
	v_add_co_u32_e32 v68, vcc, s0, v66
	s_mov_b32 s0, 0xf000
	s_nop 0
	v_addc_co_u32_e32 v69, vcc, 0, v67, vcc
	v_add_co_u32_e32 v66, vcc, s0, v66
	global_load_dwordx4 v[74:77], v[68:69], off offset:-4096 nt
	global_load_dwordx4 v[70:73], v[68:69], off nt
	v_addc_co_u32_e32 v67, vcc, 0, v67, vcc
	global_load_dwordx4 v[66:69], v[66:67], off nt
	global_load_dwordx4 v[160:163], v[224:225], off nt
	v_lshl_add_u64 v[224:225], v[224:225], 0, v[226:227]
	global_load_dwordx4 v[164:167], v[224:225], off offset:-4096 nt
	global_load_dwordx4 v[168:171], v[224:225], off nt
	v_lshl_add_u64 v[224:225], v[224:225], 0, v[226:227]
	global_load_dwordx4 v[172:175], v[224:225], off offset:-4096 nt
	global_load_dwordx4 v[176:179], v[224:225], off nt
	v_lshl_add_u64 v[224:225], v[224:225], 0, v[226:227]
	global_load_dwordx4 v[180:183], v[224:225], off offset:-4096 nt
	global_load_dwordx4 v[184:187], v[224:225], off nt
	v_lshl_add_u64 v[224:225], v[224:225], 0, v[226:227]
	global_load_dwordx4 v[188:191], v[224:225], off offset:-4096 nt
	global_load_dwordx4 v[192:195], v[224:225], off nt
	v_lshl_add_u64 v[224:225], v[224:225], 0, v[226:227]
	global_load_dwordx4 v[196:199], v[224:225], off offset:-4096 nt
	global_load_dwordx4 v[200:203], v[224:225], off nt
	v_lshl_add_u64 v[224:225], v[224:225], 0, v[226:227]
	global_load_dwordx4 v[204:207], v[224:225], off offset:-4096 nt
	global_load_dwordx4 v[208:211], v[224:225], off nt
	v_lshl_add_u64 v[224:225], v[224:225], 0, v[226:227]
	global_load_dwordx4 v[212:215], v[224:225], off offset:-4096 nt
	global_load_dwordx4 v[216:219], v[224:225], off nt
	v_mov_b32_e32 v226, 0x1000
	v_lshl_add_u64 v[224:225], v[224:225], 0, v[226:227]
	global_load_dwordx4 v[220:223], v[224:225], off nt
	s_waitcnt lgkmcnt(0)
	s_barrier
; #define LAS __attribute__((address_space(3)))
; DI unsigned pk2(float lo, float hi) { f32x2 v = {lo, hi}; return __builtin_bit_cast(unsigned, __builtin_convertvector(v, bf2_t)); }
;     DI void fused(const f32x4 (&acc)[2][2][4][2], const pg8::Unit& u, int wr, int wc, LAS unsigned char* lds) const {
;     ...
;             for (int rr = 0; rr < 16; ++rr) {
;                 const f32x4 a = *(const LAS f32x4*)(lds + (size_t)(w8 * 16 + rr) * 1040 + lane_ * 16);
;                 const f32x4 v = a + xo[rr];
;                 *(f32x4*)(xout + g0 + (size_t)rr * DM) = v;
;                 if (XB) {
;                     *(u32x2*)(XB + g0 + (size_t)rr * DM) = (u32x2){pk2(v[0], v[1]), pk2(v[2], v[3])};
;                     float part = (v[0] * v[0] + v[1] * v[1]) + (v[2] * v[2] + v[3] * v[3]);
;                     part = wave_sum(part, lane_);
;                     if (lane_ < 4) ssq_next[(size_t)(u.pm * 256 + ai * 128 + w8 * 16 + rr) * 16 + u.pn * 4 + lane_] = (lane_ == 0) ? part : 0.f;
;                 }
	v_lshl_add_u32 v0, v130, 4, 0
	s_mulk_i32 s2, 0x410
	v_add_u32_e32 v0, s2, v0
	ds_read_b128 v[134:137], v0
	s_lshl_b32 s16, s73, 2
	s_mov_b32 s86, s60
	v_readlane_b32 s60, v255, 52
	v_cmp_gt_i32_e64 s[4:5], 4, v130
	v_cmp_eq_u32_e64 s[0:1], 0, v130
	s_ashr_i32 s17, s16, 31
	v_ashrrev_i32_e32 v131, 31, v130
	s_andn2_b64 vcc, exec, s[8:9]
	s_mov_b32 s97, s94
	v_readlane_b32 s37, v255, 51
	v_readlane_b32 s61, v255, 53
	s_waitcnt vmcnt(31) lgkmcnt(0)
	v_mov_b64_e32 v[126:127], v[144:145]
	v_mov_b64_e32 v[128:129], v[146:147]
	v_pk_add_f32 v[126:127], v[126:127], v[134:135]
	v_cndmask_b32_e64 v134, 0, 1, s[8:9]
	v_pk_add_f32 v[128:129], v[128:129], v[136:137]
	v_lshl_add_u64 v[136:137], s[48:49], 0, v[142:143]
	v_cmp_ne_u32_e64 s[6:7], 1, v134
	v_lshl_add_u64 v[134:135], v[140:141], 1, s[12:13]
	global_store_dwordx4 v[136:137], v[126:129], off nt
	s_cbranch_vccnz .LBB0_589
	v_cvt_pk_bf16_f32 v140, v126, v127
	v_mul_f32_e32 v127, v127, v127
	v_fmac_f32_e32 v127, v126, v126
	v_mul_f32_e32 v126, v129, v129
	v_fmac_f32_e32 v126, v128, v128
	v_add_f32_e32 v126, v127, v126
	v_cvt_pk_bf16_f32 v141, v128, v129
	flat_store_dwordx2 v[134:135], v[140:141]
	v_add_f32_dpp v126, v126, v126 row_ror:1 row_mask:0xf bank_mask:0xf bound_ctrl:1
	s_nop 1
	v_add_f32_dpp v126, v126, v126 row_ror:2 row_mask:0xf bank_mask:0xf bound_ctrl:1
	s_nop 1
	v_add_f32_dpp v126, v126, v126 row_ror:4 row_mask:0xf bank_mask:0xf bound_ctrl:1
	s_nop 1
	v_add_f32_dpp v126, v126, v126 row_ror:8 row_mask:0xf bank_mask:0xf bound_ctrl:1
	s_nop 0
	v_readlane_b32 s24, v126, 0
	v_readlane_b32 s2, v126, 16
	v_readlane_b32 s25, v126, 32
	v_readlane_b32 s3, v126, 48
	s_and_saveexec_b64 s[22:23], s[4:5]
	s_cbranch_execz .LBB0_588
	v_mov_b32_e32 v126, s2
	v_mov_b32_e32 v127, s3
	s_lshl_b64 s[2:3], s[18:19], 6
	s_add_u32 s19, s10, s2
	s_addc_u32 s20, s11, s3
	s_lshl_b64 s[2:3], s[16:17], 2
	v_pk_add_f32 v[126:127], s[24:25], v[126:127]
	s_add_u32 s2, s19, s2
	v_add_f32_e32 v126, v126, v127
	s_addc_u32 s3, s20, s3
	v_cndmask_b32_e64 v128, 0, v126, s[0:1]
	v_lshl_add_u64 v[126:127], v[130:131], 2, s[2:3]
	flat_store_dword v[126:127], v128

; #define LAS __attribute__((address_space(3)))
; DI unsigned pk2(float lo, float hi) { f32x2 v = {lo, hi}; return __builtin_bit_cast(unsigned, __builtin_convertvector(v, bf2_t)); }
;     DI void fused(const f32x4 (&acc)[2][2][4][2], const pg8::Unit& u, int wr, int wc, LAS unsigned char* lds) const {
;     ...
;             for (int rr = 0; rr < 16; ++rr) {
;                 const f32x4 a = *(const LAS f32x4*)(lds + (size_t)(w8 * 16 + rr) * 1040 + lane_ * 16);
;                 const f32x4 v = a + xo[rr];
;                 *(f32x4*)(xout + g0 + (size_t)rr * DM) = v;
;                 if (XB) {
;                     *(u32x2*)(XB + g0 + (size_t)rr * DM) = (u32x2){pk2(v[0], v[1]), pk2(v[2], v[3])};
;                     float part = (v[0] * v[0] + v[1] * v[1]) + (v[2] * v[2] + v[3] * v[3]);
;                     part = wave_sum(part, lane_);
;                     if (lane_ < 4) ssq_next[(size_t)(u.pm * 256 + ai * 128 + w8 * 16 + rr) * 16 + u.pn * 4 + lane_] = (lane_ == 0) ? part : 0.f;
;                 }
.LBB0_589:
	ds_read_b128 v[126:129], v0 offset:1040
	s_waitcnt vmcnt(16) lgkmcnt(0)
	v_mov_b64_e32 v[122:123], v[148:149]
	v_mov_b64_e32 v[124:125], v[150:151]
	v_mov_b64_e32 v[118:119], v[152:153]
	v_mov_b64_e32 v[120:121], v[154:155]
	v_mov_b64_e32 v[114:115], v[156:157]
	v_mov_b64_e32 v[116:117], v[158:159]
	v_mov_b64_e32 v[110:111], v[228:229]
	v_mov_b64_e32 v[112:113], v[230:231]
	v_mov_b64_e32 v[106:107], v[232:233]
	v_mov_b64_e32 v[108:109], v[234:235]
	v_mov_b64_e32 v[102:103], v[236:237]
	v_mov_b64_e32 v[104:105], v[238:239]
	v_mov_b64_e32 v[98:99], v[240:241]
	v_mov_b64_e32 v[100:101], v[242:243]
	v_mov_b64_e32 v[94:95], v[244:245]
	v_mov_b64_e32 v[96:97], v[246:247]
	v_mov_b64_e32 v[90:91], v[248:249]
	v_mov_b64_e32 v[92:93], v[250:251]
	v_pk_add_f32 v[122:123], v[122:123], v[126:127]
	v_add_co_u32_e32 v126, vcc, 0x1000, v136
	v_pk_add_f32 v[124:125], v[124:125], v[128:129]
	s_nop 0
	v_addc_co_u32_e32 v127, vcc, 0, v137, vcc
	s_and_b64 vcc, exec, s[6:7]
	global_store_dwordx4 v[126:127], v[122:125], off nt
	s_cbranch_vccnz .LBB0_593
	v_cvt_pk_bf16_f32 v126, v122, v123
	v_mul_f32_e32 v123, v123, v123
	v_fmac_f32_e32 v123, v122, v122
	v_mul_f32_e32 v122, v125, v125
	v_fmac_f32_e32 v122, v124, v124
	v_add_f32_e32 v122, v123, v122
	v_cvt_pk_bf16_f32 v127, v124, v125
	flat_store_dwordx2 v[134:135], v[126:127] offset:2048
	v_add_f32_dpp v122, v122, v122 row_ror:1 row_mask:0xf bank_mask:0xf bound_ctrl:1
	s_nop 1
	v_add_f32_dpp v122, v122, v122 row_ror:2 row_mask:0xf bank_mask:0xf bound_ctrl:1
	s_nop 1
	v_add_f32_dpp v122, v122, v122 row_ror:4 row_mask:0xf bank_mask:0xf bound_ctrl:1
	s_nop 1
	v_add_f32_dpp v122, v122, v122 row_ror:8 row_mask:0xf bank_mask:0xf bound_ctrl:1
	s_nop 0
	v_readlane_b32 s24, v122, 0
	v_readlane_b32 s2, v122, 16
	v_readlane_b32 s25, v122, 32
	v_readlane_b32 s3, v122, 48
	s_and_saveexec_b64 s[22:23], s[4:5]
	s_cbranch_execz .LBB0_592
	v_mov_b32_e32 v122, s2
	s_or_b32 s2, s18, 1
	v_mov_b32_e32 v123, s3
	s_ashr_i32 s3, s2, 31
	s_lshl_b64 s[2:3], s[2:3], 6
	s_add_u32 s19, s10, s2
	s_addc_u32 s20, s11, s3
	s_lshl_b64 s[2:3], s[16:17], 2
	v_pk_add_f32 v[122:123], s[24:25], v[122:123]
	s_add_u32 s2, s19, s2
	v_add_f32_e32 v122, v122, v123
	s_addc_u32 s3, s20, s3
	v_cndmask_b32_e64 v124, 0, v122, s[0:1]
	v_lshl_add_u64 v[122:123], v[130:131], 2, s[2:3]
	flat_store_dword v[122:123], v124
